# final LN pass (layer 0): shift/scale modulation vector loads issued up front
# baseline (speedup 1.0000x reference)
.LBB0_1923:
	s_lshl_b64 s[4:5], s[8:9], 12
	s_add_u32 s8, s96, s4
	s_addc_u32 s9, s97, s5
	s_and_b64 s[4:5], s[48:49], exec
	s_cselect_b32 s9, s9, 0
	s_cselect_b32 s8, s8, 0
	s_cmp_eq_u64 s[8:9], 0
	s_cbranch_scc1 .LBB0_1907
	s_waitcnt vmcnt(7)
	v_add_f32_e32 v0, v30, v31
	v_add_f32_e32 v36, v32, v33
	v_add_f32_e32 v0, v0, v36
	s_waitcnt vmcnt(6)
	v_add_f32_e32 v36, v26, v27
	v_add_f32_e32 v37, v28, v29
	v_add_f32_e32 v0, 0, v0
	v_add_f32_e32 v36, v36, v37
	v_add_f32_e32 v0, v36, v0
	s_waitcnt vmcnt(5)
	v_add_f32_e32 v36, v22, v23
	v_add_f32_e32 v37, v24, v25
	v_add_f32_e32 v36, v36, v37
	v_add_f32_e32 v0, v36, v0
	s_waitcnt vmcnt(4)
	v_add_f32_e32 v36, v18, v19
	v_add_f32_e32 v37, v20, v21
	v_add_f32_e32 v36, v36, v37
	v_add_f32_e32 v0, v36, v0
	s_waitcnt vmcnt(3)
	v_add_f32_e32 v36, v14, v15
	v_add_f32_e32 v37, v16, v17
	v_add_f32_e32 v36, v36, v37
	v_add_f32_e32 v0, v36, v0
	s_waitcnt vmcnt(2)
	v_add_f32_e32 v36, v10, v11
	v_add_f32_e32 v37, v12, v13
	v_add_f32_e32 v36, v36, v37
	v_add_f32_e32 v0, v36, v0
	s_waitcnt vmcnt(1)
	v_add_f32_e32 v36, v6, v7
	v_add_f32_e32 v37, v8, v9
	v_add_f32_e32 v36, v36, v37
	v_add_f32_e32 v0, v36, v0
	s_waitcnt vmcnt(0)
	v_add_f32_e32 v36, v2, v3
	v_add_f32_e32 v37, v4, v5
	v_add_f32_e32 v36, v36, v37
	v_add_f32_e32 v0, v36, v0
	ds_swizzle_b32 v36, v0 offset:swizzle(SWAP,1)
	s_min_i32 s4, s6, 0x4000
	s_ashr_i32 s4, s4, 12
	s_mul_hi_i32 s5, s4, 0xc000
	s_mul_i32 s4, s4, 0xc000
	s_waitcnt lgkmcnt(0)
	v_add_f32_e32 v0, v0, v36
	ds_swizzle_b32 v36, v0 offset:swizzle(SWAP,2)
	v_readlane_b32 s10, v255, 22
	s_add_u32 s4, s10, s4
	v_readlane_b32 s10, v255, 23
	s_addc_u32 s5, s10, s5
	s_waitcnt lgkmcnt(0)
	v_add_f32_e32 v0, v0, v36
	ds_swizzle_b32 v36, v0 offset:swizzle(SWAP,4)
	s_waitcnt lgkmcnt(0)
	v_add_f32_e32 v0, v0, v36
	ds_swizzle_b32 v36, v0 offset:swizzle(SWAP,8)
	s_waitcnt lgkmcnt(0)
	v_add_f32_e32 v0, v0, v36
	ds_swizzle_b32 v36, v0 offset:swizzle(SWAP,16)
	s_waitcnt lgkmcnt(0)
	v_add_f32_e32 v0, v0, v36
	v_mov_b32_e32 v36, v0
	s_nop 1
	v_permlane32_swap_b32_e32 v0, v36
	v_add_f32_e32 v0, v0, v36
	v_fmac_f32_e32 v33, 0xba000000, v0
	v_fmac_f32_e32 v31, 0xba000000, v0
	v_fmac_f32_e32 v32, 0xba000000, v0
	v_fmac_f32_e32 v30, 0xba000000, v0
	v_mul_f32_e32 v36, v31, v31
	v_mul_f32_e32 v37, v33, v33
	v_fmac_f32_e32 v36, v30, v30
	v_fmac_f32_e32 v37, v32, v32
	v_fmac_f32_e32 v29, 0xba000000, v0
	v_fmac_f32_e32 v27, 0xba000000, v0
	v_add_f32_e32 v36, v36, v37
	v_fmac_f32_e32 v28, 0xba000000, v0
	v_fmac_f32_e32 v26, 0xba000000, v0
	v_mul_f32_e32 v37, v27, v27
	v_mul_f32_e32 v38, v29, v29
	v_fmac_f32_e32 v37, v26, v26
	v_fmac_f32_e32 v38, v28, v28
	v_add_f32_e32 v37, v37, v38
	v_fmac_f32_e32 v25, 0xba000000, v0
	v_fmac_f32_e32 v23, 0xba000000, v0
	v_add_f32_e32 v36, v36, v37
	v_fmac_f32_e32 v24, 0xba000000, v0
	v_fmac_f32_e32 v22, 0xba000000, v0
	v_mul_f32_e32 v37, v23, v23
	v_mul_f32_e32 v38, v25, v25
	v_fmac_f32_e32 v37, v22, v22
	v_fmac_f32_e32 v38, v24, v24
	v_add_f32_e32 v37, v37, v38
	v_fmac_f32_e32 v21, 0xba000000, v0
	v_fmac_f32_e32 v19, 0xba000000, v0
	v_add_f32_e32 v36, v37, v36
	v_fmac_f32_e32 v20, 0xba000000, v0
	v_fmac_f32_e32 v18, 0xba000000, v0
	v_mul_f32_e32 v37, v19, v19
	v_mul_f32_e32 v38, v21, v21
	v_fmac_f32_e32 v37, v18, v18
	v_fmac_f32_e32 v38, v20, v20
	v_add_f32_e32 v37, v37, v38
	v_fmac_f32_e32 v17, 0xba000000, v0
	v_fmac_f32_e32 v15, 0xba000000, v0
	v_add_f32_e32 v36, v37, v36
	v_fmac_f32_e32 v16, 0xba000000, v0
	v_fmac_f32_e32 v14, 0xba000000, v0
	v_mul_f32_e32 v37, v15, v15
	v_mul_f32_e32 v38, v17, v17
	v_fmac_f32_e32 v37, v14, v14
	v_fmac_f32_e32 v38, v16, v16
	v_add_f32_e32 v37, v37, v38
	v_fmac_f32_e32 v13, 0xba000000, v0
	v_fmac_f32_e32 v11, 0xba000000, v0
	v_add_f32_e32 v36, v37, v36
	v_fmac_f32_e32 v12, 0xba000000, v0
	v_fmac_f32_e32 v10, 0xba000000, v0
	v_mul_f32_e32 v37, v11, v11
	v_mul_f32_e32 v38, v13, v13
	v_fmac_f32_e32 v37, v10, v10
	v_fmac_f32_e32 v38, v12, v12
	v_add_f32_e32 v37, v37, v38
	v_fmac_f32_e32 v9, 0xba000000, v0
	v_fmac_f32_e32 v7, 0xba000000, v0
	v_add_f32_e32 v36, v37, v36
	v_fmac_f32_e32 v8, 0xba000000, v0
	v_fmac_f32_e32 v6, 0xba000000, v0
	v_mul_f32_e32 v37, v7, v7
	v_mul_f32_e32 v38, v9, v9
	v_fmac_f32_e32 v37, v6, v6
	v_fmac_f32_e32 v38, v8, v8
	v_add_f32_e32 v37, v37, v38
	v_lshl_add_u64 v[38:39], v[34:35], 2, s[4:5]
	v_add_f32_e32 v48, v37, v36
	v_add_co_u32_e32 v36, vcc, s86, v38
	global_load_dwordx4 v[44:47], v[38:39], off
	s_nop 0
	v_addc_co_u32_e32 v37, vcc, 0, v39, vcc
	global_load_dwordx4 v[40:43], v[36:37], off offset:-4096
	v_add_co_u32_e32 v196, vcc, s71, v38
	s_nop 1
	v_addc_co_u32_e32 v197, vcc, 0, v39, vcc
	global_load_dwordx4 v[130:133], v[36:37], off offset:-3072
	global_load_dwordx4 v[134:137], v[38:39], off offset:1024
	global_load_dwordx4 v[138:141], v[36:37], off offset:-2048
	global_load_dwordx4 v[142:145], v[38:39], off offset:2048
	global_load_dwordx4 v[146:149], v[36:37], off offset:-1024
	global_load_dwordx4 v[150:153], v[38:39], off offset:3072
	global_load_dwordx4 v[154:157], v[36:37], off
	global_load_dwordx4 v[158:161], v[196:197], off
	global_load_dwordx4 v[162:165], v[36:37], off offset:1024
	global_load_dwordx4 v[166:169], v[196:197], off offset:1024
	global_load_dwordx4 v[170:173], v[36:37], off offset:2048
	global_load_dwordx4 v[174:177], v[196:197], off offset:2048
	global_load_dwordx4 v[178:181], v[36:37], off offset:3072
	global_load_dwordx4 v[182:185], v[196:197], off offset:3072
	v_fmac_f32_e32 v5, 0xba000000, v0
	v_fmac_f32_e32 v3, 0xba000000, v0
	v_fmac_f32_e32 v4, 0xba000000, v0
	v_fmac_f32_e32 v2, 0xba000000, v0
	v_mul_f32_e32 v0, v3, v3
	v_mul_f32_e32 v49, v5, v5
	v_fmac_f32_e32 v0, v2, v2
	v_fmac_f32_e32 v49, v4, v4
	v_add_f32_e32 v0, v0, v49
	v_add_f32_e32 v0, v0, v48
	ds_swizzle_b32 v48, v0 offset:swizzle(SWAP,1)
	v_lshl_add_u64 v[34:35], v[34:35], 1, s[8:9]
	s_waitcnt lgkmcnt(0)
	v_add_f32_e32 v0, v0, v48
	ds_swizzle_b32 v48, v0 offset:swizzle(SWAP,2)
	s_waitcnt lgkmcnt(0)
	v_add_f32_e32 v0, v0, v48
	ds_swizzle_b32 v48, v0 offset:swizzle(SWAP,4)
	s_waitcnt lgkmcnt(0)
	v_add_f32_e32 v0, v0, v48
	ds_swizzle_b32 v48, v0 offset:swizzle(SWAP,8)
	s_waitcnt lgkmcnt(0)
	v_add_f32_e32 v0, v0, v48
	ds_swizzle_b32 v48, v0 offset:swizzle(SWAP,16)
	s_waitcnt lgkmcnt(0)
	v_add_f32_e32 v0, v0, v48
	v_mov_b32_e32 v48, v0
	s_nop 1
	v_permlane32_swap_b32_e32 v0, v48
	v_add_f32_e32 v0, v0, v48
	v_fmamk_f32 v0, v0, 0x3a000000, v254
	v_mul_f32_e32 v48, 0x4f800000, v0
	v_cmp_gt_f32_e32 vcc, s55, v0
	s_waitcnt vmcnt(0)
	v_pk_add_f32 v[42:43], v[42:43], 1.0 op_sel_hi:[1,0]
	v_cndmask_b32_e32 v0, v0, v48, vcc
	v_sqrt_f32_e32 v48, v0
	v_pk_add_f32 v[40:41], v[40:41], 1.0 op_sel_hi:[1,0]
	v_add_u32_e32 v49, -1, v48
	v_fma_f32 v50, -v49, v48, v0
	v_cmp_ge_f32_e64 s[4:5], 0, v50
	v_add_u32_e32 v50, 1, v48
	s_nop 0
	v_cndmask_b32_e64 v49, v48, v49, s[4:5]
	v_fma_f32 v48, -v50, v48, v0
	v_cmp_lt_f32_e64 s[4:5], 0, v48
	s_nop 1
	v_cndmask_b32_e64 v48, v49, v50, s[4:5]
	v_mul_f32_e32 v49, 0x37800000, v48
	v_cndmask_b32_e32 v48, v48, v49, vcc
	v_mov_b32_e32 v49, 0x260
	v_cmp_class_f32_e32 vcc, v0, v49
	s_nop 1
	v_cndmask_b32_e32 v0, v48, v0, vcc
	v_div_scale_f32 v48, s[4:5], v0, v0, 1.0
	v_rcp_f32_e32 v49, v48
	s_mov_b64 s[4:5], 0x2000
	v_fma_f32 v50, -v48, v49, 1.0
	v_fmac_f32_e32 v49, v50, v49
	v_div_scale_f32 v50, vcc, 1.0, v0, 1.0
	v_mul_f32_e32 v51, v50, v49
	v_fma_f32 v52, -v48, v51, v50
	v_fmac_f32_e32 v51, v52, v49
	v_fma_f32 v48, -v48, v51, v50
	v_div_fmas_f32 v48, v48, v49, v51
	v_div_fixup_f32 v0, v48, v0, 1.0
	v_pk_mul_f32 v[30:31], v[30:31], v[0:1] op_sel_hi:[1,0]
	v_pk_mul_f32 v[32:33], v[32:33], v[0:1] op_sel_hi:[1,0]
	v_pk_fma_f32 v[30:31], v[40:41], v[30:31], v[44:45]
	v_pk_fma_f32 v[32:33], v[42:43], v[32:33], v[46:47]
	v_cvt_pk_bf16_f32 v30, v30, v31
	v_cvt_pk_bf16_f32 v31, v32, v33
	v_lshl_add_u64 v[48:49], v[38:39], 0, s[4:5]
	global_store_dwordx2 v[34:35], v[30:31], off
	v_pk_mul_f32 v[26:27], v[26:27], v[0:1] op_sel_hi:[1,0]
	v_pk_mul_f32 v[28:29], v[28:29], v[0:1] op_sel_hi:[1,0]
	v_pk_mul_f32 v[22:23], v[22:23], v[0:1] op_sel_hi:[1,0]
	v_pk_mul_f32 v[24:25], v[24:25], v[0:1] op_sel_hi:[1,0]
	v_pk_mul_f32 v[18:19], v[18:19], v[0:1] op_sel_hi:[1,0]
	v_pk_mul_f32 v[20:21], v[20:21], v[0:1] op_sel_hi:[1,0]
	v_pk_mul_f32 v[14:15], v[14:15], v[0:1] op_sel_hi:[1,0]
	v_pk_mul_f32 v[16:17], v[16:17], v[0:1] op_sel_hi:[1,0]
	v_pk_mul_f32 v[10:11], v[10:11], v[0:1] op_sel_hi:[1,0]
	v_pk_mul_f32 v[12:13], v[12:13], v[0:1] op_sel_hi:[1,0]
	v_pk_mul_f32 v[6:7], v[6:7], v[0:1] op_sel_hi:[1,0]
	v_pk_mul_f32 v[8:9], v[8:9], v[0:1] op_sel_hi:[1,0]
	v_pk_mul_f32 v[2:3], v[2:3], v[0:1] op_sel_hi:[1,0]
	v_pk_mul_f32 v[4:5], v[4:5], v[0:1] op_sel_hi:[1,0]
	v_pk_add_f32 v[132:133], v[132:133], 1.0 op_sel_hi:[1,0]
	v_pk_add_f32 v[130:131], v[130:131], 1.0 op_sel_hi:[1,0]
	v_pk_fma_f32 v[28:29], v[132:133], v[28:29], v[136:137]
	v_pk_fma_f32 v[26:27], v[130:131], v[26:27], v[134:135]
	s_nop 0
	v_cvt_pk_bf16_f32 v26, v26, v27
	v_cvt_pk_bf16_f32 v27, v28, v29
	global_store_dwordx2 v[34:35], v[26:27], off offset:512
	v_pk_add_f32 v[140:141], v[140:141], 1.0 op_sel_hi:[1,0]
	v_pk_add_f32 v[138:139], v[138:139], 1.0 op_sel_hi:[1,0]
	v_pk_fma_f32 v[24:25], v[140:141], v[24:25], v[144:145]
	v_pk_fma_f32 v[22:23], v[138:139], v[22:23], v[142:143]
	s_nop 0
	v_cvt_pk_bf16_f32 v22, v22, v23
	v_cvt_pk_bf16_f32 v23, v24, v25
	global_store_dwordx2 v[34:35], v[22:23], off offset:1024
	v_pk_add_f32 v[148:149], v[148:149], 1.0 op_sel_hi:[1,0]
	v_pk_add_f32 v[146:147], v[146:147], 1.0 op_sel_hi:[1,0]
	v_pk_fma_f32 v[20:21], v[148:149], v[20:21], v[152:153]
	v_pk_fma_f32 v[18:19], v[146:147], v[18:19], v[150:151]
	s_nop 0
	v_cvt_pk_bf16_f32 v18, v18, v19
	v_cvt_pk_bf16_f32 v19, v20, v21
	global_store_dwordx2 v[34:35], v[18:19], off offset:1536
	v_pk_add_f32 v[156:157], v[156:157], 1.0 op_sel_hi:[1,0]
	v_pk_add_f32 v[154:155], v[154:155], 1.0 op_sel_hi:[1,0]
	v_pk_fma_f32 v[16:17], v[156:157], v[16:17], v[160:161]
	v_pk_fma_f32 v[14:15], v[154:155], v[14:15], v[158:159]
	s_nop 0
	v_cvt_pk_bf16_f32 v14, v14, v15
	v_cvt_pk_bf16_f32 v15, v16, v17
	global_store_dwordx2 v[34:35], v[14:15], off offset:2048
	v_pk_add_f32 v[164:165], v[164:165], 1.0 op_sel_hi:[1,0]
	v_pk_add_f32 v[162:163], v[162:163], 1.0 op_sel_hi:[1,0]
	v_pk_fma_f32 v[12:13], v[164:165], v[12:13], v[168:169]
	v_pk_fma_f32 v[10:11], v[162:163], v[10:11], v[166:167]
	s_nop 0
	v_cvt_pk_bf16_f32 v10, v10, v11
	v_cvt_pk_bf16_f32 v11, v12, v13
	global_store_dwordx2 v[34:35], v[10:11], off offset:2560
	v_pk_add_f32 v[172:173], v[172:173], 1.0 op_sel_hi:[1,0]
	v_pk_add_f32 v[170:171], v[170:171], 1.0 op_sel_hi:[1,0]
	v_pk_fma_f32 v[8:9], v[172:173], v[8:9], v[176:177]
	v_pk_fma_f32 v[6:7], v[170:171], v[6:7], v[174:175]
	s_nop 0
	v_cvt_pk_bf16_f32 v6, v6, v7
	v_cvt_pk_bf16_f32 v7, v8, v9
	global_store_dwordx2 v[34:35], v[6:7], off offset:3072
	v_pk_add_f32 v[180:181], v[180:181], 1.0 op_sel_hi:[1,0]
	v_pk_add_f32 v[178:179], v[178:179], 1.0 op_sel_hi:[1,0]
	v_pk_fma_f32 v[4:5], v[180:181], v[4:5], v[184:185]
	v_pk_fma_f32 v[2:3], v[178:179], v[2:3], v[182:183]
	s_nop 0
	v_cvt_pk_bf16_f32 v2, v2, v3
	v_cvt_pk_bf16_f32 v3, v4, v5
	global_store_dwordx2 v[34:35], v[2:3], off offset:3584
	s_branch .LBB0_1907
